# replace cooperative-groups grid.sync at seam 0 by split-phase arrive + XCD-hierarchical barrier (barrier words zeroed at kernel start)
# speedup vs baseline: 1.0133x; 1.0115x over previous
_Z8mega_fwd6Paramsii:
	s_load_dwordx16 s[4:19], s[0:1], 0x0
	v_and_b32_e32 v188, 0x3ff, v0
	v_writelane_b32 v249, s2, 0
	s_load_dword s2, s[0:1], 0xe0
	s_load_dwordx4 s[28:31], s[0:1], 0xc0
	s_load_dwordx2 s[96:97], s[0:1], 0xd8
	s_waitcnt lgkmcnt(0)
	v_writelane_b32 v249, s4, 1
	v_cmp_gt_u32_e32 vcc, 2, v188
	s_nop 0
	v_writelane_b32 v249, s5, 2
	v_writelane_b32 v249, s6, 3
	v_writelane_b32 v249, s7, 4
	v_writelane_b32 v249, s8, 5
	v_writelane_b32 v249, s9, 6
	v_writelane_b32 v249, s10, 7
	v_writelane_b32 v249, s11, 8
	v_writelane_b32 v249, s12, 9
	v_writelane_b32 v249, s13, 10
	v_writelane_b32 v249, s14, 11
	v_writelane_b32 v249, s15, 12
	v_writelane_b32 v249, s16, 13
	v_writelane_b32 v249, s17, 14
	v_writelane_b32 v249, s18, 15
	v_writelane_b32 v249, s19, 16
	s_add_u32 s4, s0, 0xd8
	s_addc_u32 s5, s1, 0
	v_writelane_b32 v249, s2, 17
	s_and_saveexec_b64 s[2:3], vcc
	v_lshl_add_u32 v1, v188, 2, 0
	v_add_u32_e32 v1, 0x23fe0, v1
	v_mov_b32_e32 v2, 0
	ds_write_b32 v1, v2
	s_or_b64 exec, exec, s[2:3]
	s_load_dwordx2 s[24:25], s[0:1], 0xd0
	s_add_u32 s2, s30, 0x310000
	s_addc_u32 s3, s31, 0
	v_writelane_b32 v249, s2, 18
	s_waitcnt lgkmcnt(0)
	s_cmp_lt_i32 s24, 1
	v_writelane_b32 v249, s3, 19
	s_cselect_b64 s[6:7], -1, 0
	s_mov_b32 s2, 0
	s_cmp_gt_i32 s24, 0
	v_writelane_b32 v249, s2, 20
	s_cselect_b64 s[2:3], -1, 0
	s_cmp_lt_i32 s25, 1
	s_cselect_b64 s[8:9], -1, 0
	s_or_b64 s[2:3], s[2:3], s[8:9]
	s_and_b64 vcc, exec, s[2:3]
	s_barrier
	s_cbranch_vccnz .LBB0_53
	s_load_dwordx2 s[100:101], s[0:1], 0x130
	v_readlane_b32 s32, v249, 0
	s_cmp_gt_u32 s32, 6
	s_cbranch_scc1 .Ls0_arrive
	s_lshl_b32 s33, s32, 9
	v_add_u32_e32 v4, s33, v188
	v_readlane_b32 s36, v249, 18
	v_readlane_b32 s37, v249, 19
	v_cmp_gt_u32_e32 vcc, 0xd80, v4
	s_and_saveexec_b64 s[34:35], vcc
	v_lshlrev_b32_e32 v4, 2, v4
	v_mov_b32_e32 v5, 0
	s_nop 1
	global_store_dword v4, v5, s[36:37]
	s_or_b64 exec, exec, s[34:35]
	s_waitcnt vmcnt(0)
	s_barrier
	v_readfirstlane_b32 s33, v188
	s_cmp_lg_u32 s33, 0
	s_cbranch_scc1 .Ls0_arrive
	buffer_wbl2 sc1
	s_waitcnt vmcnt(0)
.Ls0_arrive:
	v_readfirstlane_b32 s33, v188
	s_cmp_lg_u32 s33, 0
	s_cbranch_scc1 .Ls0_arrived
	s_mov_b64 s[34:35], exec
	s_mov_b64 exec, 1
	s_waitcnt lgkmcnt(0)
	v_mov_b32_e32 v4, 0
	v_mov_b32_e32 v6, 1
	global_load_dword v5, v4, s[100:101] offset:40
	global_atomic_add v6, v4, v6, s[100:101] offset:32 sc0
	s_waitcnt vmcnt(0)
	v_add_u32_e32 v7, -1, v5
	v_and_b32_e32 v8, 0xffff, v6
	v_and_b32_e32 v7, 0xffff, v7
	v_and_b32_e32 v6, 0xffff0000, v6
	v_cmp_eq_u32_e32 vcc, v8, v7
	v_readfirstlane_b32 s98, v6
	s_cbranch_vccz .Ls0_notlast
	v_sub_u32_e32 v5, 0x10000, v5
	global_atomic_add v4, v5, s[100:101] offset:32
.Ls0_notlast:
	s_mov_b64 exec, s[34:35]
.Ls0_arrived:
	v_readlane_b32 s10, v249, 0
	s_cmp_lt_i32 s10, 0
	s_cselect_b64 s[2:3], -1, 0
	s_cmp_ge_i32 s10, s96
	s_cselect_b64 s[8:9], -1, 0
	s_or_b64 s[2:3], s[2:3], s[8:9]
	v_and_b32_e32 v2, 63, v188
	s_and_b64 vcc, exec, s[2:3]
	s_cbranch_vccnz .LBB0_26
	v_lshrrev_b32_e32 v3, 6, v188
	v_lshl_add_u32 v1, s10, 3, v3
	s_movk_i32 s2, 0x500
	v_cmp_gt_u32_e32 vcc, s2, v1
	s_and_saveexec_b64 s[8:9], vcc
	s_cbranch_execz .LBB0_25
	s_load_dwordx16 s[36:51], s[0:1], 0x0
	v_lshlrev_b32_e32 v6, 3, v188
	v_lshlrev_b32_e32 v12, 14, v3
	v_lshrrev_b32_e32 v3, 3, v2
	v_and_b32_e32 v6, 56, v6
	v_add_u32_e32 v5, 0, v12
	v_and_b32_e32 v8, 31, v188
	v_mul_u32_u24_e32 v7, 0x84, v6
	v_lshlrev_b32_e32 v9, 2, v3
	v_lshlrev_b32_e32 v10, 1, v6
	v_mov_b32_e32 v11, 0
	v_lshrrev_b32_e32 v4, 5, v2
	v_add3_u32 v5, v5, v7, v9
	v_lshl_add_u64 v[6:7], s[30:31], 0, v[10:11]
	s_lshl_b32 s14, s96, 3
	v_lshlrev_b32_e32 v10, 2, v8
	s_mov_b64 s[2:3], 0x400000
	s_waitcnt lgkmcnt(0)
	s_cmp_lg_u64 s[48:49], 0
	v_lshl_add_u64 v[8:9], s[50:51], 0, v[10:11]
	v_mul_u32_u24_e32 v11, 0x84, v4
	v_lshl_add_u64 v[6:7], v[6:7], 0, s[2:3]
	s_cselect_b64 s[2:3], -1, 0
	v_or_b32_e32 v11, v12, v11
	v_add3_u32 v25, v11, v10, 0
	s_add_u32 s12, s48, 56
	v_cndmask_b32_e64 v10, 0, 1, s[2:3]
	v_or_b32_e32 v22, 8, v3
	v_or_b32_e32 v23, 16, v3
	v_or_b32_e32 v24, 24, v3
	s_mov_b64 s[10:11], 0
	s_addc_u32 s13, s49, 0
	s_mov_b32 s15, 0x66666667
	s_movk_i32 s16, 0x50
	v_cmp_ne_u32_e64 s[2:3], 1, v10
	s_movk_i32 s17, 0x2800
	s_movk_i32 s18, 0x4ff
	s_branch .LBB0_7

.LBB0_36:
	s_or_b64 exec, exec, s[2:3]
	s_movk_i32 s2, 0xd80
	v_cmp_gt_i32_e32 vcc, s2, v2
	s_and_saveexec_b64 s[10:11], vcc
	s_branch .LBB0_44
	v_cvt_f32_u32_e32 v1, s8
	v_add_u32_e32 v3, s8, v2
	v_mov_b32_e32 v4, s8
	v_cmp_gt_i32_e32 vcc, s2, v3
	v_rcp_iflag_f32_e32 v1, v1
	s_sub_i32 s9, 0, s8
	v_max_i32_e32 v5, 0xd80, v3
	v_addc_co_u32_e64 v4, s[2:3], v2, v4, vcc
	v_mul_f32_e32 v1, 0x4f7ffffe, v1
	v_cvt_u32_f32_e32 v1, v1
	v_sub_u32_e32 v4, v5, v4
	s_mov_b64 s[12:13], -1
	v_mul_lo_u32 v5, s9, v1
	v_mul_hi_u32 v5, v1, v5
	v_add_u32_e32 v1, v1, v5
	v_mul_hi_u32 v1, v4, v1
	v_mul_lo_u32 v5, v1, s8
	v_sub_u32_e32 v4, v4, v5
	v_add_u32_e32 v6, 1, v1
	v_cmp_le_u32_e64 s[2:3], s8, v4
	v_subrev_u32_e32 v5, s8, v4
	s_nop 0
	v_cndmask_b32_e64 v1, v1, v6, s[2:3]
	v_cndmask_b32_e64 v4, v4, v5, s[2:3]
	v_add_u32_e32 v5, 1, v1
	v_cmp_le_u32_e64 s[2:3], s8, v4
	v_mov_b32_e32 v4, v2
	s_nop 0
	v_cndmask_b32_e64 v1, v1, v5, s[2:3]
	v_addc_co_u32_e32 v1, vcc, 1, v1, vcc
	v_cmp_lt_u32_e32 vcc, 1, v1
	s_and_saveexec_b64 s[2:3], vcc
	s_cbranch_execz .LBB0_41
	v_and_b32_e32 v6, -2, v1
	s_lshl_b32 s9, s96, 10
	v_readlane_b32 s16, v249, 18
	s_mov_b32 s14, s9
	s_mov_b64 s[12:13], 0
	v_mov_b32_e32 v7, 0
	v_mov_b32_e32 v8, v6
	v_mov_b64_e32 v[4:5], v[2:3]
	v_readlane_b32 s17, v249, 19

.LBB0_53:
	s_cmp_gt_i32 s25, 1
	s_cselect_b64 s[2:3], -1, 0
	s_and_b64 s[6:7], s[6:7], s[2:3]
	s_andn2_b64 vcc, exec, s[6:7]
	s_cbranch_vccnz .LBB0_68
	v_readfirstlane_b32 s32, v188
	s_cmp_lg_u32 s32, 0
	s_cbranch_scc1 .Ls0_waitdone
	s_mov_b64 s[34:35], exec
	s_mov_b64 exec, 1
	v_mov_b32_e32 v4, 0
.Ls0_spin:
	global_load_dword v5, v4, s[100:101] offset:32 sc1
	s_waitcnt vmcnt(0)
	v_and_b32_e32 v5, 0xffff0000, v5
	v_cmp_ne_u32_e32 vcc, s98, v5
	s_cbranch_vccnz .Ls0_spun
	s_sleep 1
	s_branch .Ls0_spin

.Ls0_waitdone:
	s_getreg_b32 s4, hwreg(HW_REG_XCC_ID, 0, 4)
	s_and_b32 s4, s4, 15
	v_cmp_eq_u32_e32 vcc, 0, v188
	v_writelane_b32 v249, s4, 20
	s_and_saveexec_b64 s[4:5], vcc
	s_cbranch_execz .LBB0_67
	s_mov_b64 s[6:7], exec
	v_mbcnt_lo_u32_b32 v0, s6, 0
	v_mbcnt_hi_u32_b32 v0, s7, v0
	v_cmp_eq_u32_e32 vcc, 0, v0
	s_and_b64 s[8:9], exec, vcc
	s_mov_b64 exec, s[8:9]
	s_cbranch_execz .LBB0_67
	v_readlane_b32 s8, v249, 20
	s_bcnt1_i32_b64 s6, s[6:7]
	s_lshl_b32 s8, s8, 8
	v_mov_b32_e32 v1, s6
	v_readlane_b32 s6, v249, 18
	v_mov_b32_e32 v0, s8
	v_readlane_b32 s7, v249, 19
	s_nop 4
	global_atomic_add v0, v1, s[6:7] offset:1024
.LBB0_67:
	s_or_b64 exec, exec, s[4:5]
	v_writelane_b32 v249, s96, 39
	v_writelane_b32 v249, s97, 40
	s_mov_b32 s36, s2
	s_mov_b32 s37, s3
	s_mov_b32 s38, s20
	s_mov_b32 s39, s21
	s_mov_b32 s42, s22
	s_mov_b32 s43, s24
	s_mov_b32 s44, s25
	s_mov_b32 s45, s26
	s_mov_b32 s46, s86
	s_mov_b32 s47, s88
	s_mov_b32 s48, s96
	s_mov_b32 s49, s97
	s_waitcnt vmcnt(0)
	v_cmp_eq_u32_e32 vcc, 0, v188
	s_waitcnt vmcnt(0)
	s_barrier
	s_and_saveexec_b64 s[2:3], vcc
	s_cbranch_execz .Ls0b_428
	s_add_i32 s4, 0, 0x23fe0
	v_mov_b32_e32 v0, s4
	s_waitcnt vmcnt(0) expcnt(0) lgkmcnt(0)
	ds_read_b32 v2, v0
	s_add_i32 s4, 0, 0x23fe4
	v_mov_b32_e32 v0, s4
	ds_read_b32 v0, v0
	s_waitcnt lgkmcnt(1)
	v_cmp_ne_u32_e32 vcc, 0, v2
	s_cbranch_vccnz .Ls0b_396
	v_readlane_b32 s4, v249, 17
	s_mul_i32 s24, s97, s4
	s_add_u32 s4, s30, 0x310200
	s_addc_u32 s5, s31, 0
	s_add_u32 s6, s30, 0x310400
	s_addc_u32 s7, s31, 0
	s_add_u32 s8, s30, 0x310500
	s_addc_u32 s9, s31, 0
	s_add_u32 s10, s30, 0x310600
	s_addc_u32 s11, s31, 0
	s_add_u32 s12, s30, 0x310700
	s_addc_u32 s13, s31, 0
	s_add_u32 s14, s30, 0x310800
	s_addc_u32 s15, s31, 0
	s_add_u32 s16, s30, 0x310900
	s_addc_u32 s17, s31, 0
	s_add_u32 s18, s30, 0x310a00
	s_addc_u32 s19, s31, 0
	s_add_u32 s20, s30, 0x310b00
	s_addc_u32 s21, s31, 0
	s_add_u32 s22, s30, 0x310c00
	s_addc_u32 s23, s31, 0
	s_add_u32 s34, s30, 0x310d00
	s_addc_u32 s35, s31, 0
	s_add_u32 s60, s30, 0x310e00
	s_addc_u32 s61, s31, 0
	s_add_u32 s62, s30, 0x310f00
	s_addc_u32 s63, s31, 0
	s_add_u32 s84, s30, 0x311000
	s_addc_u32 s85, s31, 0
	s_add_u32 s86, s30, 0x311100
	s_addc_u32 s87, s31, 0
	s_add_u32 s88, s30, 0x311200
	s_addc_u32 s89, s31, 0
	s_add_u32 s90, s30, 0x311300
	s_mul_i32 s24, s24, s96
	s_addc_u32 s91, s31, 0
	s_mov_b32 s25, 1
	v_mov_b32_e32 v16, 0
	s_branch .Ls0b_384

.Ls0b_428:
	s_or_b64 exec, exec, s[2:3]
	s_waitcnt lgkmcnt(0)
	s_barrier
	s_mov_b32 s2, s36
	s_mov_b32 s3, s37
	s_mov_b32 s20, s38
	s_mov_b32 s21, s39
	s_mov_b32 s22, s42
	s_mov_b32 s24, s43
	s_mov_b32 s25, s44
	s_mov_b32 s26, s45
	s_mov_b32 s86, s46
	s_mov_b32 s88, s47
	s_mov_b32 s96, s48
	s_mov_b32 s97, s49

	.amdhsa_kernel _Z8mega_fwd6Paramsii
		.amdhsa_group_segment_fixed_size 0
		.amdhsa_private_segment_fixed_size 0
		.amdhsa_kernarg_size 472
		.amdhsa_user_sgpr_count 2
		.amdhsa_user_sgpr_dispatch_ptr 0
		.amdhsa_user_sgpr_queue_ptr 0
		.amdhsa_user_sgpr_kernarg_segment_ptr 1
		.amdhsa_user_sgpr_dispatch_id 0
		.amdhsa_user_sgpr_kernarg_preload_length 0
		.amdhsa_user_sgpr_kernarg_preload_offset 0
		.amdhsa_user_sgpr_private_segment_size 0
		.amdhsa_uses_dynamic_stack 0
		.amdhsa_enable_private_segment 0
		.amdhsa_system_sgpr_workgroup_id_x 1
		.amdhsa_system_sgpr_workgroup_id_y 0
		.amdhsa_system_sgpr_workgroup_id_z 0
		.amdhsa_system_sgpr_workgroup_info 0
		.amdhsa_system_vgpr_workitem_id 2
		.amdhsa_next_free_vgpr 250
		.amdhsa_next_free_sgpr 102
		.amdhsa_accum_offset 252
		.amdhsa_reserve_vcc 1
		.amdhsa_float_round_mode_32 0
		.amdhsa_float_round_mode_16_64 0
		.amdhsa_float_denorm_mode_32 3
		.amdhsa_float_denorm_mode_16_64 3
		.amdhsa_dx10_clamp 1
		.amdhsa_ieee_mode 1
		.amdhsa_fp16_overflow 0
		.amdhsa_tg_split 0
		.amdhsa_exception_fp_ieee_invalid_op 0
		.amdhsa_exception_fp_denorm_src 0
		.amdhsa_exception_fp_ieee_div_zero 0
		.amdhsa_exception_fp_ieee_overflow 0
		.amdhsa_exception_fp_ieee_underflow 0
		.amdhsa_exception_fp_ieee_inexact 0
		.amdhsa_exception_int_div_zero 0
	.end_amdhsa_kernel

amdhsa.kernels:
  - .agpr_count:     0
    .args:
      - .offset:         0
        .size:           208
        .value_kind:     by_value
      - .offset:         208
        .size:           4
        .value_kind:     by_value
      - .offset:         212
        .size:           4
        .value_kind:     by_value
      - .offset:         216
        .size:           4
        .value_kind:     hidden_block_count_x
      - .offset:         220
        .size:           4
        .value_kind:     hidden_block_count_y
      - .offset:         224
        .size:           4
        .value_kind:     hidden_block_count_z
      - .offset:         228
        .size:           2
        .value_kind:     hidden_group_size_x
      - .offset:         230
        .size:           2
        .value_kind:     hidden_group_size_y
      - .offset:         232
        .size:           2
        .value_kind:     hidden_group_size_z
      - .offset:         234
        .size:           2
        .value_kind:     hidden_remainder_x
      - .offset:         236
        .size:           2
        .value_kind:     hidden_remainder_y
      - .offset:         238
        .size:           2
        .value_kind:     hidden_remainder_z
      - .offset:         256
        .size:           8
        .value_kind:     hidden_global_offset_x
      - .offset:         264
        .size:           8
        .value_kind:     hidden_global_offset_y
      - .offset:         272
        .size:           8
        .value_kind:     hidden_global_offset_z
      - .offset:         280
        .size:           2
        .value_kind:     hidden_grid_dims
      - .offset:         304
        .size:           8
        .value_kind:     hidden_multigrid_sync_arg
      - .offset:         336
        .size:           4
        .value_kind:     hidden_dynamic_lds_size
    .group_segment_fixed_size: 0
    .kernarg_segment_align: 8
    .kernarg_segment_size: 472
    .language:       OpenCL C
    .language_version:
      - 2
      - 0
    .max_flat_workgroup_size: 512
    .name:           _Z8mega_fwd6Paramsii
    .private_segment_fixed_size: 0
    .sgpr_count:     108
    .sgpr_spill_count: 72
    .symbol:         _Z8mega_fwd6Paramsii.kd
    .uniform_work_group_size: 1
    .uses_dynamic_stack: false
    .vgpr_count:     250
    .vgpr_spill_count: 0
    .wavefront_size: 64
